# unreachable old weight-conversion blocks in P2b and P7 deleted (alignment anchors keep all hot-loop phases)
# baseline (speedup 1.0000x reference)
.LBB0_373:
	s_or_b64 exec, exec, s[30:31]
	v_readlane_b32 s0, v253, 0
	v_readlane_b32 s1, v253, 1
	s_add_i32 s0, s45, 1
	v_writelane_b32 v255, s0, 29
	s_cmp_lg_u32 s45, 3
	s_cselect_b64 s[4:5], -1, 0
	v_writelane_b32 v255, s1, 30
	v_readlane_b32 s0, v254, 11
	v_readlane_b32 s1, v254, 12
	v_writelane_b32 v255, s4, 31
	s_and_b64 s[0:1], s[0:1], s[4:5]
	v_mov_b32_e32 v26, v170
	v_readlane_b32 s2, v253, 2
	v_readlane_b32 s3, v253, 3
	v_writelane_b32 v255, s5, 32
	s_and_b64 vcc, exec, s[0:1]
	s_waitcnt lgkmcnt(0)
	s_barrier
	s_branch .LBB0_438
	.p2align 6
	s_nop 0
	s_nop 0
	s_nop 0
	s_nop 0
	s_nop 0
	s_nop 0

.LBB0_950:
	s_or_b64 exec, exec, s[6:7]
	v_readlane_b32 s0, v253, 4
	v_readlane_b32 s1, v253, 5
	s_andn2_b64 vcc, exec, s[0:1]
	s_branch .LBB0_982
.LBB0_982:
	v_readlane_b32 s0, v255, 31
	v_readlane_b32 s1, v255, 32
	s_andn2_b64 vcc, exec, s[0:1]
	s_cbranch_vccz .LBB0_983
	s_getpc_b64 s[98:99]
